# natten: accumulator top copy dropped from the active path, skipped tiles carry only v[66:73]; bias loads paired into ds_read2_b32
# speedup vs baseline: 1.0027x; 1.0027x over previous
.LBB0_347:
	s_mov_b32 s99, 0
	s_bitcmp1_b32 s85, 0
	s_cselect_b32 s3, 0x2c00, 0
	s_cmp_gt_i32 s85, s97
	s_mov_b64 s[86:87], -1
	s_cbranch_scc1 .LBB0_435
	v_add_u32_e32 v2, s85, v195
	v_cmp_ge_u32_e32 vcc, v2, v194
	v_cmp_lt_u32_e64 s[86:87], v2, v214
	v_mov_b32_e32 v221, v163
	v_mov_b32_e32 v166, v0
	v_mov_b32_e32 v222, v220
	v_mov_b32_e32 v162, v219
	s_and_b64 vcc, vcc, s[86:87]
	s_and_saveexec_b64 s[86:87], vcc
	s_cbranch_execz .Lnat_inactive
	v_lshl_add_u32 v162, s3, 1, v215
	ds_read_b128 v[2:5], v162
	ds_read_b128 v[22:25], v162 offset:32
	ds_read_b128 v[54:57], v192 offset:47104
	ds_read_b128 v[58:61], v192 offset:47136
	s_waitcnt lgkmcnt(3)
	v_mfma_f32_32x32x16_bf16 v[38:53], v[2:5], v[130:133], 0
	s_waitcnt lgkmcnt(1)
	v_mfma_f32_32x32x16_bf16 v[6:21], v[2:5], v[54:57], 0
	ds_read_b128 v[2:5], v162 offset:64
	ds_read_b128 v[62:65], v192 offset:47168
	v_mfma_f32_32x32x16_bf16 v[38:53], v[22:25], v[134:137], v[38:53]
	s_waitcnt lgkmcnt(2)
	v_mfma_f32_32x32x16_bf16 v[6:21], v[22:25], v[58:61], v[6:21]
	s_waitcnt lgkmcnt(1)
	v_mfma_f32_32x32x16_bf16 v[38:53], v[2:5], v[138:141], v[38:53]
	s_waitcnt lgkmcnt(0)
	v_mfma_f32_32x32x16_bf16 v[6:21], v[2:5], v[62:65], v[6:21]
	ds_read_b128 v[2:5], v162 offset:96
	ds_read_b128 v[164:167], v192 offset:47200
	s_waitcnt lgkmcnt(1)
	v_mfma_f32_32x32x16_bf16 v[38:53], v[2:5], v[142:145], v[38:53]
	s_waitcnt lgkmcnt(0)
	v_mfma_f32_32x32x16_bf16 v[6:21], v[2:5], v[164:167], v[6:21]
	ds_read_b128 v[2:5], v162 offset:4608
	s_waitcnt lgkmcnt(0)
	v_mfma_f32_32x32x16_bf16 v[22:37], v[2:5], v[130:133], 0
	v_mfma_f32_32x32x16_bf16 v[2:17], v[2:5], v[54:57], 0
	ds_read_b128 v[54:57], v162 offset:4640
	s_waitcnt lgkmcnt(0)
	v_mfma_f32_32x32x16_bf16 v[22:37], v[54:57], v[134:137], v[22:37]
	v_mfma_f32_32x32x16_bf16 v[2:17], v[54:57], v[58:61], v[2:17]
	ds_read_b128 v[54:57], v162 offset:4672
	s_waitcnt lgkmcnt(0)
	v_mfma_f32_32x32x16_bf16 v[22:37], v[54:57], v[138:141], v[22:37]
	v_mfma_f32_32x32x16_bf16 v[2:17], v[54:57], v[62:65], v[2:17]
	ds_read_b128 v[54:57], v162 offset:4704
	s_waitcnt lgkmcnt(0)
	v_mfma_f32_32x32x16_bf16 v[22:37], v[54:57], v[142:145], v[22:37]
	v_mfma_f32_32x32x16_bf16 v[2:17], v[54:57], v[164:167], v[2:17]
	s_nop 10
	v_mov_b32_e32 v35, 0xff800000
	ds_read2_b32 v[26:27], v218 offset0:9 offset1:8
	ds_read2_b32 v[28:29], v218 offset0:11 offset1:10
	ds_read2_b32 v[30:31], v218 offset0:17 offset1:16
	ds_read2_b32 v[32:33], v218 offset0:19 offset1:18
	ds_read_b32 v34, v218 offset:172
	ds_read_b32 v162, v218 offset:100
	ds_read_b32 v164, v218 offset:96
	ds_read_b32 v166, v218 offset:132
	ds_read_b32 v177, v218 offset:104
	ds_read2_b32 v[178:179], v218 offset0:27 offset1:32
	ds_read_b32 v181, v218 offset:136
	ds_read2_b32 v[182:183], v218 offset0:35 offset1:40
	ds_read2_b32 v[184:185], v218 offset0:41 offset1:42
	s_waitcnt lgkmcnt(0)
	v_add_f32_e32 v27, v38, v27
	v_add_f32_e32 v26, v39, v26
	v_add_f32_e32 v29, v40, v29
	v_add_f32_e32 v28, v41, v28
	v_add_f32_e32 v31, v42, v31
	v_add_f32_e32 v30, v43, v30
	v_add_f32_e32 v33, v44, v33
	v_add_f32_e32 v32, v45, v32
	v_add_f32_e32 v164, v46, v164
	v_add_f32_e32 v162, v47, v162
	v_add_f32_e32 v177, v48, v177
	v_add_f32_e32 v178, v49, v178
	v_add_f32_e32 v179, v50, v179
	v_add_f32_e32 v166, v51, v166
	v_add_f32_e32 v181, v52, v181
	v_add_f32_e32 v182, v53, v182
	v_add_f32_e32 v183, v22, v183
	v_add_f32_e32 v184, v23, v184
	v_add_f32_e32 v185, v24, v185
	v_add_f32_e32 v23, v25, v34
	v_cndmask_b32_e64 v27, v35, v27, s[0:1]
	v_cndmask_b32_e64 v26, v35, v26, s[4:5]
	v_cndmask_b32_e64 v29, v35, v29, s[6:7]
	v_cndmask_b32_e64 v28, v35, v28, s[8:9]
	v_cndmask_b32_e64 v31, v35, v31, s[10:11]
	v_cndmask_b32_e64 v30, v35, v30, s[12:13]
	v_cndmask_b32_e64 v33, v35, v33, s[14:15]
	v_cndmask_b32_e64 v32, v35, v32, s[16:17]
	v_cndmask_b32_e64 v164, v35, v164, s[18:19]
	v_cndmask_b32_e64 v162, v35, v162, s[20:21]
	v_cndmask_b32_e64 v177, v35, v177, s[22:23]
	v_cndmask_b32_e64 v178, v35, v178, s[24:25]
	v_cndmask_b32_e64 v179, v35, v179, s[26:27]
	v_cndmask_b32_e64 v166, v35, v166, s[28:29]
	v_cndmask_b32_e64 v181, v35, v181, s[30:31]
	v_cndmask_b32_e64 v182, v35, v182, s[34:35]
	v_cndmask_b32_e64 v183, v35, v183, s[36:37]
	v_cndmask_b32_e64 v184, v35, v184, s[38:39]
	v_cndmask_b32_e64 v185, v35, v185, s[40:41]
	v_cndmask_b32_e64 v23, v35, v23, s[42:43]
	v_and_b32_e32 v24, 64, v200
	v_xor_b32_e32 v22, 32, v200
	v_add_u32_e32 v24, 64, v24
	v_cmp_lt_i32_e32 vcc, v22, v24
	s_nop 1
	v_cndmask_b32_e32 v22, v200, v22, vcc
	v_lshlrev_b32_e32 v22, 2, v22
	v_max3_f32 v24, v27, v26, v29
	v_max3_f32 v24, v24, v28, v31
	v_max3_f32 v24, v24, v30, v33
	v_max3_f32 v24, v24, v32, v164
	v_max3_f32 v24, v24, v162, v177
	v_max3_f32 v24, v24, v178, v179
	v_max3_f32 v24, v24, v166, v181
	v_max3_f32 v24, v24, v182, v183
	v_max3_f32 v24, v24, v184, v185
	s_mov_b32 s88, 0xff800000
	v_max3_f32 v24, v24, v23, s88
	ds_bpermute_b32 v25, v22, v24
	v_mov_b64_e32 v[34:35], v[98:99]
	v_mov_b64_e32 v[50:51], v[114:115]
	v_mov_b64_e32 v[36:37], v[100:101]
	v_mov_b64_e32 v[38:39], v[102:103]
	s_waitcnt lgkmcnt(0)
	v_max_f32_e32 v25, v25, v25
	v_max_f32_e32 v24, v24, v25
	v_cmp_gt_f32_e32 vcc, v24, v163
	v_mov_b64_e32 v[40:41], v[104:105]
	v_mov_b64_e32 v[42:43], v[106:107]
	v_mov_b64_e32 v[44:45], v[108:109]
	v_mov_b64_e32 v[46:47], v[110:111]
	v_mov_b64_e32 v[48:49], v[112:113]
	v_mov_b64_e32 v[52:53], v[116:117]
	v_mov_b64_e32 v[54:55], v[118:119]
	v_mov_b64_e32 v[56:57], v[120:121]
	v_mov_b64_e32 v[58:59], v[122:123]
	v_mov_b64_e32 v[60:61], v[124:125]
	v_mov_b64_e32 v[62:63], v[126:127]
	v_mov_b64_e32 v[64:65], v[128:129]
	v_mov_b32_e32 v165, v220
	v_mov_b32_e32 v221, v163
	s_cbranch_vccz .LBB0_391
	v_max_f32_e32 v24, v24, v24
	v_max_f32_e32 v25, v163, v163
	v_max_f32_e32 v221, v25, v24
	v_sub_f32_e32 v24, v163, v221
	v_exp_f32_e32 v24, v24
	s_nop 0
	v_mul_f32_e32 v165, v220, v24
	v_pk_mul_f32 v[64:65], v[128:129], v[24:25] op_sel_hi:[1,0]
	v_pk_mul_f32 v[62:63], v[126:127], v[24:25] op_sel_hi:[1,0]
	v_pk_mul_f32 v[60:61], v[124:125], v[24:25] op_sel_hi:[1,0]
	v_pk_mul_f32 v[58:59], v[122:123], v[24:25] op_sel_hi:[1,0]
	v_pk_mul_f32 v[56:57], v[120:121], v[24:25] op_sel_hi:[1,0]
	v_pk_mul_f32 v[54:55], v[118:119], v[24:25] op_sel_hi:[1,0]
	v_pk_mul_f32 v[52:53], v[116:117], v[24:25] op_sel_hi:[1,0]
	v_pk_mul_f32 v[50:51], v[114:115], v[24:25] op_sel_hi:[1,0]
	v_pk_mul_f32 v[48:49], v[112:113], v[24:25] op_sel_hi:[1,0]
	v_pk_mul_f32 v[46:47], v[110:111], v[24:25] op_sel_hi:[1,0]
	v_pk_mul_f32 v[44:45], v[108:109], v[24:25] op_sel_hi:[1,0]
	v_pk_mul_f32 v[42:43], v[106:107], v[24:25] op_sel_hi:[1,0]
	v_pk_mul_f32 v[40:41], v[104:105], v[24:25] op_sel_hi:[1,0]
	v_pk_mul_f32 v[38:39], v[102:103], v[24:25] op_sel_hi:[1,0]
	v_pk_mul_f32 v[36:37], v[100:101], v[24:25] op_sel_hi:[1,0]
	v_pk_mul_f32 v[34:35], v[98:99], v[24:25] op_sel_hi:[1,0]
.LBB0_391:
	v_sub_f32_e32 v24, v27, v221
	v_exp_f32_e32 v167, v24
	v_sub_f32_e32 v24, v26, v221
	v_exp_f32_e32 v168, v24
	v_sub_f32_e32 v24, v29, v221
	v_exp_f32_e32 v169, v24
	v_sub_f32_e32 v24, v28, v221
	v_exp_f32_e32 v170, v24
	v_sub_f32_e32 v24, v31, v221
	v_exp_f32_e32 v171, v24
	v_sub_f32_e32 v24, v30, v221
	v_exp_f32_e32 v172, v24
	v_sub_f32_e32 v24, v33, v221
	v_exp_f32_e32 v173, v24
	v_sub_f32_e32 v24, v32, v221
	v_exp_f32_e32 v174, v24
	v_sub_f32_e32 v24, v164, v221
	v_exp_f32_e32 v175, v24
	v_sub_f32_e32 v24, v162, v221
	v_lshl_add_u32 v180, s3, 1, v216
	v_exp_f32_e32 v176, v24
	v_sub_f32_e32 v24, v177, v221
	v_exp_f32_e32 v177, v24
	v_sub_f32_e32 v24, v178, v221
	v_add_u32_e32 v162, 0x3000, v180
	v_exp_f32_e32 v178, v24
	ds_read2_b64 v[24:27], v162 offset0:128 offset1:130
	v_sub_f32_e32 v28, v179, v221
	v_exp_f32_e32 v179, v28
	v_cvt_pk_bf16_f32 v28, v167, v168
	v_cvt_pk_bf16_f32 v29, v169, v170
	v_cvt_pk_bf16_f32 v30, v171, v172
	v_cvt_pk_bf16_f32 v31, v173, v174
	v_add_u32_e32 v164, 0x4000, v180
	ds_read2_b64 v[186:189], v164 offset0:192 offset1:194
	s_waitcnt lgkmcnt(1)
	v_mfma_f32_32x32x16_bf16 v[50:65], v[24:27], v[28:31], v[50:65]
	v_sub_f32_e32 v24, v166, v221
	v_exp_f32_e32 v180, v24
	v_sub_f32_e32 v24, v181, v221
	v_exp_f32_e32 v181, v24
	v_sub_f32_e32 v24, v182, v221
	v_exp_f32_e32 v182, v24
	ds_read2_b64 v[24:27], v162 offset0:132 offset1:134
	s_waitcnt lgkmcnt(1)
	v_mfma_f32_32x32x16_bf16 v[34:49], v[186:189], v[28:31], v[34:49]
	v_sub_f32_e32 v28, v183, v221
	v_exp_f32_e32 v183, v28
	v_cvt_pk_bf16_f32 v28, v175, v176
	v_cvt_pk_bf16_f32 v29, v177, v178
	v_cvt_pk_bf16_f32 v30, v179, v180
	v_cvt_pk_bf16_f32 v31, v181, v182
	ds_read2_b64 v[222:225], v164 offset0:196 offset1:198
	v_sub_f32_e32 v23, v23, v221
	s_waitcnt lgkmcnt(1)
	v_mfma_f32_32x32x16_bf16 v[50:65], v[24:27], v[28:31], v[50:65]
	v_sub_f32_e32 v24, v184, v221
	v_exp_f32_e32 v184, v24
	v_sub_f32_e32 v24, v185, v221
	v_exp_f32_e32 v185, v24
	ds_read2_b64 v[24:27], v162 offset0:136 offset1:138
	v_exp_f32_e32 v186, v23
	v_sub_f32_e32 v23, 0xff800000, v221
	v_exp_f32_e32 v187, v23
	s_waitcnt lgkmcnt(1)
	v_mfma_f32_32x32x16_bf16 v[34:49], v[222:225], v[28:31], v[34:49]
	v_cvt_pk_bf16_f32 v28, v183, v184
	v_cvt_pk_bf16_f32 v29, v185, v186
	v_cvt_pk_bf16_f32 v30, v187, v187
	v_mov_b32_e32 v31, v30
	v_mov_b32_e32 v188, 0xff800000
	s_waitcnt lgkmcnt(0)
	v_mfma_f32_32x32x16_bf16 v[50:65], v[24:27], v[28:31], v[50:65]
	ds_read2_b64 v[24:27], v164 offset0:200 offset1:202
	s_waitcnt lgkmcnt(0)
	v_mfma_f32_32x32x16_bf16 v[34:49], v[24:27], v[28:31], v[34:49]
	v_mov_b32_e32 v23, 0xff800000
	ds_read2_b32 v[188:189], v218 offset0:1 offset1:0
	ds_read2_b32 v[208:209], v218 offset0:3 offset1:2
	ds_read_b32 v212, v218 offset:68
	ds_read_b32 v223, v218 offset:36
	ds_read2_b32 v[224:225], v218 offset0:19 offset1:8
	ds_read2_b32 v[226:227], v218 offset0:27 offset1:18
	ds_read2_b32 v[228:229], v218 offset0:33 offset1:25
	ds_read2_b32 v[230:231], v218 offset0:32 offset1:11
	ds_read2_b32 v[232:233], v218 offset0:35 offset1:10
	ds_read2_b32 v[234:235], v218 offset0:26 offset1:24
	ds_read2_b32 v[236:237], v218 offset0:34 offset1:16
	s_waitcnt lgkmcnt(0)
	v_add_f32_e32 v189, v18, v189
	v_add_f32_e32 v188, v19, v188
	v_add_f32_e32 v209, v20, v209
	v_add_f32_e32 v208, v21, v208
	v_add_f32_e32 v225, v2, v225
	v_add_f32_e32 v223, v3, v223
	v_add_f32_e32 v233, v4, v233
	v_add_f32_e32 v231, v5, v231
	v_add_f32_e32 v237, v6, v237
	v_add_f32_e32 v212, v7, v212
	v_add_f32_e32 v227, v8, v227
	v_add_f32_e32 v224, v9, v224
	v_add_f32_e32 v235, v10, v235
	v_add_f32_e32 v229, v11, v229
	v_add_f32_e32 v234, v12, v234
	v_add_f32_e32 v226, v13, v226
	v_add_f32_e32 v230, v14, v230
	v_add_f32_e32 v228, v15, v228
	v_add_f32_e32 v236, v16, v236
	v_add_f32_e32 v232, v17, v232
	v_cndmask_b32_e64 v189, v23, v189, s[44:45]
	v_cndmask_b32_e64 v188, v23, v188, s[46:47]
	v_cndmask_b32_e64 v209, v23, v209, s[48:49]
	v_cndmask_b32_e64 v208, v23, v208, s[50:51]
	v_cndmask_b32_e64 v225, v23, v225, s[52:53]
	v_cndmask_b32_e64 v223, v23, v223, s[54:55]
	v_cndmask_b32_e64 v233, v23, v233, s[56:57]
	v_cndmask_b32_e64 v231, v23, v231, s[58:59]
	v_cndmask_b32_e64 v237, v23, v237, s[60:61]
	v_cndmask_b32_e64 v212, v23, v212, s[62:63]
	v_cndmask_b32_e64 v227, v23, v227, s[64:65]
	v_cndmask_b32_e64 v224, v23, v224, s[66:67]
	v_cndmask_b32_e64 v235, v23, v235, s[68:69]
	v_cndmask_b32_e64 v229, v23, v229, s[70:71]
	v_cndmask_b32_e64 v234, v23, v234, s[72:73]
	v_cndmask_b32_e64 v226, v23, v226, s[74:75]
	v_cndmask_b32_e64 v230, v23, v230, s[76:77]
	v_cndmask_b32_e64 v228, v23, v228, s[78:79]
	v_cndmask_b32_e64 v236, v23, v236, s[80:81]
	v_cndmask_b32_e64 v232, v23, v232, s[82:83]
	v_max3_f32 v2, v189, s88, v188
	v_max3_f32 v2, v2, v209, v208
	v_max3_f32 v2, v2, v225, v223
	v_max3_f32 v2, v2, v233, v231
	v_max3_f32 v2, v2, v237, v212
	v_max3_f32 v2, v2, v227, v224
	v_max3_f32 v2, v2, v235, v229
	v_max3_f32 v2, v2, v234, v226
	v_max3_f32 v2, v2, v230, v228
	v_max3_f32 v2, v2, v236, v232
	ds_bpermute_b32 v3, v22, v2
	v_mov_b64_e32 v[18:19], v[82:83]
	v_mov_b64_e32 v[20:21], v[84:85]
	v_mov_b64_e32 v[22:23], v[86:87]
	v_mov_b64_e32 v[24:25], v[88:89]
	s_waitcnt lgkmcnt(0)
	v_max_f32_e32 v3, v3, v3
	v_max_f32_e32 v222, v2, v3
	v_mov_b64_e32 v[2:3], v[66:67]
	v_cmp_gt_f32_e32 vcc, v222, v0
	v_mov_b64_e32 v[4:5], v[68:69]
	v_mov_b64_e32 v[6:7], v[70:71]
	v_mov_b64_e32 v[8:9], v[72:73]
	v_mov_b64_e32 v[10:11], v[74:75]
	v_mov_b64_e32 v[12:13], v[76:77]
	v_mov_b64_e32 v[14:15], v[78:79]
	v_mov_b64_e32 v[16:17], v[80:81]
	v_mov_b64_e32 v[26:27], v[90:91]
	v_mov_b64_e32 v[28:29], v[92:93]
	v_mov_b64_e32 v[30:31], v[94:95]
	v_mov_b64_e32 v[32:33], v[96:97]
	v_mov_b32_e32 v238, v219
	v_mov_b32_e32 v166, v0
	s_cbranch_vccz .LBB0_433
	v_max_f32_e32 v2, v222, v222
	v_max_f32_e32 v3, v0, v0
	v_max_f32_e32 v166, v3, v2
	v_sub_f32_e32 v2, v0, v166
	v_exp_f32_e32 v2, v2
	s_nop 0
	v_mul_f32_e32 v238, v219, v2
	v_pk_mul_f32 v[32:33], v[96:97], v[2:3] op_sel_hi:[1,0]
	v_pk_mul_f32 v[30:31], v[94:95], v[2:3] op_sel_hi:[1,0]
	v_pk_mul_f32 v[28:29], v[92:93], v[2:3] op_sel_hi:[1,0]
	v_pk_mul_f32 v[26:27], v[90:91], v[2:3] op_sel_hi:[1,0]
	v_pk_mul_f32 v[24:25], v[88:89], v[2:3] op_sel_hi:[1,0]
	v_pk_mul_f32 v[22:23], v[86:87], v[2:3] op_sel_hi:[1,0]
	v_pk_mul_f32 v[20:21], v[84:85], v[2:3] op_sel_hi:[1,0]
	v_pk_mul_f32 v[18:19], v[82:83], v[2:3] op_sel_hi:[1,0]
	v_pk_mul_f32 v[16:17], v[80:81], v[2:3] op_sel_hi:[1,0]
	v_pk_mul_f32 v[14:15], v[78:79], v[2:3] op_sel_hi:[1,0]
	v_pk_mul_f32 v[12:13], v[76:77], v[2:3] op_sel_hi:[1,0]
	v_pk_mul_f32 v[10:11], v[74:75], v[2:3] op_sel_hi:[1,0]
	v_pk_mul_f32 v[8:9], v[72:73], v[2:3] op_sel_hi:[1,0]
	v_pk_mul_f32 v[6:7], v[70:71], v[2:3] op_sel_hi:[1,0]
	v_pk_mul_f32 v[4:5], v[68:69], v[2:3] op_sel_hi:[1,0]
	v_pk_mul_f32 v[2:3], v[66:67], v[2:3] op_sel_hi:[1,0]

.LBB0_447:
	v_add_u32_e32 v218, 0x7c, v218
	s_andn2_b64 vcc, exec, s[86:87]
	s_add_i32 s84, s84, 64
	s_waitcnt lgkmcnt(0)
	s_barrier
	s_cbranch_vccz .LBB0_319
	s_cmp_eq_u32 s99, 1
	s_cbranch_scc1 .Lnat_skipcopy
	v_mov_b64_e32 v[80:81], v[16:17]
	v_mov_b64_e32 v[96:97], v[32:33]
	v_mov_b64_e32 v[112:113], v[48:49]
	v_mov_b64_e32 v[128:129], v[64:65]
	v_mov_b64_e32 v[78:79], v[14:15]
	v_mov_b64_e32 v[76:77], v[12:13]
	v_mov_b64_e32 v[74:75], v[10:11]
	v_mov_b64_e32 v[94:95], v[30:31]
	v_mov_b64_e32 v[92:93], v[28:29]
	v_mov_b64_e32 v[90:91], v[26:27]
	v_mov_b64_e32 v[88:89], v[24:25]
	v_mov_b64_e32 v[86:87], v[22:23]
	v_mov_b64_e32 v[84:85], v[20:21]
	v_mov_b64_e32 v[82:83], v[18:19]
	v_mov_b64_e32 v[110:111], v[46:47]
	v_mov_b64_e32 v[108:109], v[44:45]
	v_mov_b64_e32 v[106:107], v[42:43]
	v_mov_b64_e32 v[104:105], v[40:41]
	v_mov_b64_e32 v[102:103], v[38:39]
	v_mov_b64_e32 v[100:101], v[36:37]
	v_mov_b64_e32 v[98:99], v[34:35]
	v_mov_b64_e32 v[126:127], v[62:63]
	v_mov_b64_e32 v[124:125], v[60:61]
	v_mov_b64_e32 v[122:123], v[58:59]
	v_mov_b64_e32 v[120:121], v[56:57]
	v_mov_b64_e32 v[118:119], v[54:55]
	v_mov_b64_e32 v[116:117], v[52:53]
	v_mov_b64_e32 v[114:115], v[50:51]
.Lnat_skipcopy:
	v_mov_b64_e32 v[72:73], v[8:9]
	v_mov_b64_e32 v[70:71], v[6:7]
	v_mov_b64_e32 v[68:69], v[4:5]
	v_mov_b64_e32 v[66:67], v[2:3]
	v_mov_b32_e32 v219, v162
	v_mov_b32_e32 v220, v222
	s_mov_b32 s85, s3
	v_mov_b32_e32 v163, v221
	v_mov_b32_e32 v0, v166
	s_branch .LBB0_347
.Lnat_inactive:
	s_or_b64 exec, exec, s[86:87]
	v_mov_b64_e32 v[2:3], v[66:67]
	v_mov_b64_e32 v[4:5], v[68:69]
	v_mov_b64_e32 v[6:7], v[70:71]
	v_mov_b64_e32 v[8:9], v[72:73]
	s_mov_b32 s99, 1
	s_branch .LBB0_434
